# ph_prep staging: lane-disjoint WAW waits in front of the predicated loads removed (4 loads per trip in flight instead of 1)
# speedup vs baseline: 1.0324x; 1.0022x over previous
; __device__ __forceinline__ void ph_prep(bf16_t* Z, const bf16_t* WUQ, const bf16_t* WUKV, const bf16_t* D64, const float* qkq, const float* qkk,
;                                         bf16_t* Q, bf16_t* Kb, bf16_t* Vb, bf16_t* F1lat, bf16_t* F1ctx, unsigned char* lds_) { PH_IDS;
;     ...
;         for (int hf = 0; hf < 3; ++hf) { pg8::u32x4 st[4];
; #pragma unroll
;           for (int i = 0; i < 4; ++i) { const int e = tid_ + NT * (4 * hf + i);
;               if (e < 1440) st[i] = *(const pg8::u32x4*)(Z + (size_t)(row0 + e / 20) * ZW + C_KVC + (e % 20) * 8);
;               else if (e < 3744) st[i] = *(const pg8::u32x4*)(Z + (size_t)(row0 + ((e - 1440) >> 5)) * ZW + C_QC + ((e - 1440) & 31) * 8);
;               else if (e < 6048) st[i] = *(const pg8::u32x4*)(Z + (size_t)(row0 + ((e - 3744) >> 5)) * ZW + C_FU + ((e - 3744) & 31) * 8); }
.LBB0_409:
	v_add_u32_e32 v18, s34, v99
	v_cmp_lt_i32_e32 vcc, s44, v18
	s_and_saveexec_b64 s[8:9], vcc
	s_xor_b64 s[10:11], exec, s[8:9]
	s_cbranch_execz .LBB0_417
	v_cmp_lt_u32_e64 s[8:9], s45, v18
	s_and_saveexec_b64 s[12:13], s[8:9]
	s_xor_b64 s[12:13], exec, s[12:13]
	s_cbranch_execz .LBB0_414
	v_cmp_gt_u32_e64 s[8:9], s46, v18
	s_and_saveexec_b64 s[14:15], s[8:9]
	s_cbranch_execz .LBB0_413
	v_add_u32_e32 v2, 0xfffff160, v18
	v_lshrrev_b32_e32 v2, 5, v2
	v_add_u32_e32 v2, s57, v2
	v_ashrrev_i32_e32 v3, 31, v2
	v_lshlrev_b64 v[2:3], 12, v[2:3]
	v_lshl_add_u64 v[2:3], v[124:125], 0, v[2:3]
	global_load_dwordx4 v[2:5], v[2:3], off offset:2368

; __device__ __forceinline__ void ph_prep(bf16_t* Z, const bf16_t* WUQ, const bf16_t* WUKV, const bf16_t* D64, const float* qkq, const float* qkk,
;                                         bf16_t* Q, bf16_t* Kb, bf16_t* Vb, bf16_t* F1lat, bf16_t* F1ctx, unsigned char* lds_) { PH_IDS;
;     ...
;         for (int hf = 0; hf < 3; ++hf) { pg8::u32x4 st[4];
; #pragma unroll
;           for (int i = 0; i < 4; ++i) { const int e = tid_ + NT * (4 * hf + i);
;               if (e < 1440) st[i] = *(const pg8::u32x4*)(Z + (size_t)(row0 + e / 20) * ZW + C_KVC + (e % 20) * 8);
;               else if (e < 3744) st[i] = *(const pg8::u32x4*)(Z + (size_t)(row0 + ((e - 1440) >> 5)) * ZW + C_QC + ((e - 1440) & 31) * 8);
;               else if (e < 6048) st[i] = *(const pg8::u32x4*)(Z + (size_t)(row0 + ((e - 3744) >> 5)) * ZW + C_FU + ((e - 3744) & 31) * 8); }
.LBB0_414:
	s_andn2_saveexec_b64 s[8:9], s[12:13]
	s_cbranch_execz .LBB0_416
	v_add_u32_e32 v2, 0xfffffa60, v18
	v_lshrrev_b32_e32 v2, 5, v2
	v_add_u32_e32 v2, s57, v2
	v_ashrrev_i32_e32 v3, 31, v2
	v_lshlrev_b64 v[2:3], 12, v[2:3]
	v_lshl_add_u64 v[2:3], v[124:125], 0, v[2:3]
	global_load_dwordx4 v[2:5], v[2:3], off offset:1856

; __device__ __forceinline__ void ph_prep(bf16_t* Z, const bf16_t* WUQ, const bf16_t* WUKV, const bf16_t* D64, const float* qkq, const float* qkk,
;                                         bf16_t* Q, bf16_t* Kb, bf16_t* Vb, bf16_t* F1lat, bf16_t* F1ctx, unsigned char* lds_) { PH_IDS;
;     ...
;         for (int hf = 0; hf < 3; ++hf) { pg8::u32x4 st[4];
; #pragma unroll
;           for (int i = 0; i < 4; ++i) { const int e = tid_ + NT * (4 * hf + i);
;               if (e < 1440) st[i] = *(const pg8::u32x4*)(Z + (size_t)(row0 + e / 20) * ZW + C_KVC + (e % 20) * 8);
;               else if (e < 3744) st[i] = *(const pg8::u32x4*)(Z + (size_t)(row0 + ((e - 1440) >> 5)) * ZW + C_QC + ((e - 1440) & 31) * 8);
;               else if (e < 6048) st[i] = *(const pg8::u32x4*)(Z + (size_t)(row0 + ((e - 3744) >> 5)) * ZW + C_FU + ((e - 3744) & 31) * 8); }
.LBB0_417:
	s_or_saveexec_b64 s[8:9], s[10:11]
	v_mul_hi_i32 v19, v18, s47
	v_lshrrev_b32_e32 v21, 31, v19
	v_ashrrev_i32_e32 v23, 3, v19
	s_xor_b64 exec, exec, s[8:9]
	s_cbranch_execz .LBB0_419
	v_add_u32_e32 v4, v23, v21
	v_add_u32_e32 v2, s57, v4
	v_mul_lo_u32 v4, v4, 20
	v_ashrrev_i32_e32 v3, 31, v2
	v_sub_u32_e32 v4, v18, v4
	v_lshlrev_b64 v[2:3], 12, v[2:3]
	v_lshlrev_b32_e32 v4, 3, v4
	v_lshl_add_u64 v[2:3], s[20:21], 0, v[2:3]
	v_ashrrev_i32_e32 v5, 31, v4
	v_lshl_add_u64 v[2:3], v[4:5], 1, v[2:3]
	global_load_dwordx4 v[2:5], v[2:3], off
.LBB0_419:
	s_or_b64 exec, exec, s[8:9]
	v_add_u32_e32 v19, 0x200, v18
	v_cmp_lt_i32_e64 s[8:9], s44, v19
	s_and_saveexec_b64 s[10:11], s[8:9]
	s_xor_b64 s[12:13], exec, s[10:11]
	s_cbranch_execz .LBB0_427
	v_cmp_lt_u32_e64 s[10:11], s45, v19
	s_and_saveexec_b64 s[14:15], s[10:11]
	s_xor_b64 s[14:15], exec, s[14:15]
	s_cbranch_execz .LBB0_424
	v_cmp_gt_u32_e64 s[10:11], s46, v19
	s_and_saveexec_b64 s[16:17], s[10:11]
	s_cbranch_execz .LBB0_423
	v_add_u32_e32 v6, 0xfffff360, v18
	v_lshrrev_b32_e32 v6, 5, v6
	v_add_u32_e32 v6, s57, v6
	v_ashrrev_i32_e32 v7, 31, v6
	v_lshlrev_b64 v[6:7], 12, v[6:7]
	v_lshl_add_u64 v[6:7], v[124:125], 0, v[6:7]
	global_load_dwordx4 v[6:9], v[6:7], off offset:2368

; __device__ __forceinline__ void ph_prep(bf16_t* Z, const bf16_t* WUQ, const bf16_t* WUKV, const bf16_t* D64, const float* qkq, const float* qkk,
;                                         bf16_t* Q, bf16_t* Kb, bf16_t* Vb, bf16_t* F1lat, bf16_t* F1ctx, unsigned char* lds_) { PH_IDS;
;     ...
;         for (int hf = 0; hf < 3; ++hf) { pg8::u32x4 st[4];
; #pragma unroll
;           for (int i = 0; i < 4; ++i) { const int e = tid_ + NT * (4 * hf + i);
;               if (e < 1440) st[i] = *(const pg8::u32x4*)(Z + (size_t)(row0 + e / 20) * ZW + C_KVC + (e % 20) * 8);
;               else if (e < 3744) st[i] = *(const pg8::u32x4*)(Z + (size_t)(row0 + ((e - 1440) >> 5)) * ZW + C_QC + ((e - 1440) & 31) * 8);
;               else if (e < 6048) st[i] = *(const pg8::u32x4*)(Z + (size_t)(row0 + ((e - 3744) >> 5)) * ZW + C_FU + ((e - 3744) & 31) * 8); }
.LBB0_424:
	s_andn2_saveexec_b64 s[10:11], s[14:15]
	s_cbranch_execz .LBB0_426
	v_add_u32_e32 v6, 0xfffffc60, v18
	v_lshrrev_b32_e32 v6, 5, v6
	v_add_u32_e32 v6, s57, v6
	v_ashrrev_i32_e32 v7, 31, v6
	v_lshlrev_b64 v[6:7], 12, v[6:7]
	v_lshl_add_u64 v[6:7], v[124:125], 0, v[6:7]
	global_load_dwordx4 v[6:9], v[6:7], off offset:1856

; __device__ __forceinline__ void ph_prep(bf16_t* Z, const bf16_t* WUQ, const bf16_t* WUKV, const bf16_t* D64, const float* qkq, const float* qkk,
;                                         bf16_t* Q, bf16_t* Kb, bf16_t* Vb, bf16_t* F1lat, bf16_t* F1ctx, unsigned char* lds_) { PH_IDS;
;     ...
;         for (int hf = 0; hf < 3; ++hf) { pg8::u32x4 st[4];
; #pragma unroll
;           for (int i = 0; i < 4; ++i) { const int e = tid_ + NT * (4 * hf + i);
;               if (e < 1440) st[i] = *(const pg8::u32x4*)(Z + (size_t)(row0 + e / 20) * ZW + C_KVC + (e % 20) * 8);
;               else if (e < 3744) st[i] = *(const pg8::u32x4*)(Z + (size_t)(row0 + ((e - 1440) >> 5)) * ZW + C_QC + ((e - 1440) & 31) * 8);
;               else if (e < 6048) st[i] = *(const pg8::u32x4*)(Z + (size_t)(row0 + ((e - 3744) >> 5)) * ZW + C_FU + ((e - 3744) & 31) * 8); }
.LBB0_427:
	s_or_saveexec_b64 s[10:11], s[12:13]
	v_mul_hi_i32 v20, v19, s47
	v_lshrrev_b32_e32 v24, 31, v20
	v_ashrrev_i32_e32 v25, 3, v20
	s_xor_b64 exec, exec, s[10:11]
	s_cbranch_execz .LBB0_429
	v_add_u32_e32 v8, v25, v24
	v_add_u32_e32 v6, s57, v8
	v_mul_lo_u32 v8, v8, 20
	v_ashrrev_i32_e32 v7, 31, v6
	v_sub_u32_e32 v8, v19, v8
	v_lshlrev_b64 v[6:7], 12, v[6:7]
	v_lshlrev_b32_e32 v8, 3, v8
	v_lshl_add_u64 v[6:7], s[20:21], 0, v[6:7]
	v_ashrrev_i32_e32 v9, 31, v8
	v_lshl_add_u64 v[6:7], v[8:9], 1, v[6:7]
	global_load_dwordx4 v[6:9], v[6:7], off
.LBB0_429:
	s_or_b64 exec, exec, s[10:11]
	v_add_u32_e32 v20, 0x400, v18
	v_cmp_lt_i32_e64 s[10:11], s44, v20
	s_and_saveexec_b64 s[12:13], s[10:11]
	s_xor_b64 s[14:15], exec, s[12:13]
	s_cbranch_execz .LBB0_437
	v_cmp_lt_u32_e64 s[12:13], s45, v20
	s_and_saveexec_b64 s[16:17], s[12:13]
	s_xor_b64 s[16:17], exec, s[16:17]
	s_cbranch_execz .LBB0_434
	v_cmp_gt_u32_e64 s[12:13], s46, v20
	s_and_saveexec_b64 s[18:19], s[12:13]
	s_cbranch_execz .LBB0_433
	v_add_u32_e32 v10, 0xfffff560, v18
	v_lshrrev_b32_e32 v10, 5, v10
	v_add_u32_e32 v10, s57, v10
	v_ashrrev_i32_e32 v11, 31, v10
	v_lshlrev_b64 v[10:11], 12, v[10:11]
	v_lshl_add_u64 v[10:11], v[124:125], 0, v[10:11]
	global_load_dwordx4 v[10:13], v[10:11], off offset:2368

; __device__ __forceinline__ void ph_prep(bf16_t* Z, const bf16_t* WUQ, const bf16_t* WUKV, const bf16_t* D64, const float* qkq, const float* qkk,
;                                         bf16_t* Q, bf16_t* Kb, bf16_t* Vb, bf16_t* F1lat, bf16_t* F1ctx, unsigned char* lds_) { PH_IDS;
;     ...
;         for (int hf = 0; hf < 3; ++hf) { pg8::u32x4 st[4];
; #pragma unroll
;           for (int i = 0; i < 4; ++i) { const int e = tid_ + NT * (4 * hf + i);
;               if (e < 1440) st[i] = *(const pg8::u32x4*)(Z + (size_t)(row0 + e / 20) * ZW + C_KVC + (e % 20) * 8);
;               else if (e < 3744) st[i] = *(const pg8::u32x4*)(Z + (size_t)(row0 + ((e - 1440) >> 5)) * ZW + C_QC + ((e - 1440) & 31) * 8);
;               else if (e < 6048) st[i] = *(const pg8::u32x4*)(Z + (size_t)(row0 + ((e - 3744) >> 5)) * ZW + C_FU + ((e - 3744) & 31) * 8); }
.LBB0_434:
	s_andn2_saveexec_b64 s[12:13], s[16:17]
	s_cbranch_execz .LBB0_436
	v_add_u32_e32 v10, 0xfffffe60, v18
	v_lshrrev_b32_e32 v10, 5, v10
	v_add_u32_e32 v10, s57, v10
	v_ashrrev_i32_e32 v11, 31, v10
	v_lshlrev_b64 v[10:11], 12, v[10:11]
	v_lshl_add_u64 v[10:11], v[124:125], 0, v[10:11]
	global_load_dwordx4 v[10:13], v[10:11], off offset:1856

; __device__ __forceinline__ void ph_prep(bf16_t* Z, const bf16_t* WUQ, const bf16_t* WUKV, const bf16_t* D64, const float* qkq, const float* qkk,
;                                         bf16_t* Q, bf16_t* Kb, bf16_t* Vb, bf16_t* F1lat, bf16_t* F1ctx, unsigned char* lds_) { PH_IDS;
;     ...
;         for (int hf = 0; hf < 3; ++hf) { pg8::u32x4 st[4];
; #pragma unroll
;           for (int i = 0; i < 4; ++i) { const int e = tid_ + NT * (4 * hf + i);
;               if (e < 1440) st[i] = *(const pg8::u32x4*)(Z + (size_t)(row0 + e / 20) * ZW + C_KVC + (e % 20) * 8);
;               else if (e < 3744) st[i] = *(const pg8::u32x4*)(Z + (size_t)(row0 + ((e - 1440) >> 5)) * ZW + C_QC + ((e - 1440) & 31) * 8);
;               else if (e < 6048) st[i] = *(const pg8::u32x4*)(Z + (size_t)(row0 + ((e - 3744) >> 5)) * ZW + C_FU + ((e - 3744) & 31) * 8); }
.LBB0_437:
	s_or_saveexec_b64 s[12:13], s[14:15]
	v_mul_hi_i32 v22, v20, s47
	v_lshrrev_b32_e32 v26, 31, v22
	v_ashrrev_i32_e32 v27, 3, v22
	s_xor_b64 exec, exec, s[12:13]
	s_cbranch_execz .LBB0_439
	v_add_u32_e32 v12, v27, v26
	v_add_u32_e32 v10, s57, v12
	v_mul_lo_u32 v12, v12, 20
	v_ashrrev_i32_e32 v11, 31, v10
	v_sub_u32_e32 v12, v20, v12
	v_lshlrev_b64 v[10:11], 12, v[10:11]
	v_lshlrev_b32_e32 v12, 3, v12
	v_lshl_add_u64 v[10:11], s[20:21], 0, v[10:11]
	v_ashrrev_i32_e32 v13, 31, v12
	v_lshl_add_u64 v[10:11], v[12:13], 1, v[10:11]
	global_load_dwordx4 v[10:13], v[10:11], off
.LBB0_439:
	s_or_b64 exec, exec, s[12:13]
	v_add_u32_e32 v22, 0x600, v18
	v_cmp_lt_i32_e64 s[12:13], s44, v22
	s_and_saveexec_b64 s[14:15], s[12:13]
	s_xor_b64 s[16:17], exec, s[14:15]
	s_cbranch_execz .LBB0_447
	v_cmp_lt_u32_e64 s[14:15], s45, v22
	s_and_saveexec_b64 s[18:19], s[14:15]
	s_xor_b64 s[18:19], exec, s[18:19]
	s_cbranch_execz .LBB0_444
	v_cmp_gt_u32_e64 s[14:15], s46, v22
	s_and_saveexec_b64 s[30:31], s[14:15]
	s_cbranch_execz .LBB0_443
	v_add_u32_e32 v14, 0xfffff760, v18
	v_lshrrev_b32_e32 v14, 5, v14
	v_add_u32_e32 v14, s57, v14
	v_ashrrev_i32_e32 v15, 31, v14
	v_lshlrev_b64 v[14:15], 12, v[14:15]
	v_lshl_add_u64 v[14:15], v[124:125], 0, v[14:15]
	global_load_dwordx4 v[14:17], v[14:15], off offset:2368

; __device__ __forceinline__ void ph_prep(bf16_t* Z, const bf16_t* WUQ, const bf16_t* WUKV, const bf16_t* D64, const float* qkq, const float* qkk,
;                                         bf16_t* Q, bf16_t* Kb, bf16_t* Vb, bf16_t* F1lat, bf16_t* F1ctx, unsigned char* lds_) { PH_IDS;
;     ...
;         for (int hf = 0; hf < 3; ++hf) { pg8::u32x4 st[4];
; #pragma unroll
;           for (int i = 0; i < 4; ++i) { const int e = tid_ + NT * (4 * hf + i);
;               if (e < 1440) st[i] = *(const pg8::u32x4*)(Z + (size_t)(row0 + e / 20) * ZW + C_KVC + (e % 20) * 8);
;               else if (e < 3744) st[i] = *(const pg8::u32x4*)(Z + (size_t)(row0 + ((e - 1440) >> 5)) * ZW + C_QC + ((e - 1440) & 31) * 8);
;               else if (e < 6048) st[i] = *(const pg8::u32x4*)(Z + (size_t)(row0 + ((e - 3744) >> 5)) * ZW + C_FU + ((e - 3744) & 31) * 8); }
.LBB0_444:
	s_andn2_saveexec_b64 s[14:15], s[18:19]
	s_cbranch_execz .LBB0_446
	v_add_u32_e32 v14, 0x60, v18
	v_lshrrev_b32_e32 v14, 5, v14
	v_add_u32_e32 v14, s57, v14
	v_ashrrev_i32_e32 v15, 31, v14
	v_lshlrev_b64 v[14:15], 12, v[14:15]
	v_lshl_add_u64 v[14:15], v[124:125], 0, v[14:15]
	global_load_dwordx4 v[14:17], v[14:15], off offset:1856

; #define LAS __attribute__((address_space(3)))
; __device__ __forceinline__ void ph_prep(bf16_t* Z, const bf16_t* WUQ, const bf16_t* WUKV, const bf16_t* D64, const float* qkq, const float* qkk,
;                                         bf16_t* Q, bf16_t* Kb, bf16_t* Vb, bf16_t* F1lat, bf16_t* F1ctx, unsigned char* lds_) { PH_IDS;
;     ...
;         for (int hf = 0; hf < 3; ++hf) { pg8::u32x4 st[4];
; #pragma unroll
;           for (int i = 0; i < 4; ++i) { const int e = tid_ + NT * (4 * hf + i);
;               if (e < 1440) st[i] = *(const pg8::u32x4*)(Z + (size_t)(row0 + e / 20) * ZW + C_KVC + (e % 20) * 8);
;               else if (e < 3744) st[i] = *(const pg8::u32x4*)(Z + (size_t)(row0 + ((e - 1440) >> 5)) * ZW + C_QC + ((e - 1440) & 31) * 8);
;               else if (e < 6048) st[i] = *(const pg8::u32x4*)(Z + (size_t)(row0 + ((e - 3744) >> 5)) * ZW + C_FU + ((e - 3744) & 31) * 8); }
; #pragma unroll
;           for (int i = 0; i < 4; ++i) { const int e = tid_ + NT * (4 * hf + i);
;               if (e < 1440) *(LAS pg8::u32x4*)(sm + O_KV + (e / 20) * P_KV + (e % 20) * 16) = st[i];
;               else if (e < 3744) *(LAS pg8::u32x4*)(sm + O_QC + ((e - 1440) >> 5) * P_QC + ((e - 1440) & 31) * 16) = st[i];
;               else if (e < 6048) *(LAS pg8::u32x4*)(sm + O_FU + ((e - 3744) >> 5) * P_QC + ((e - 3744) & 31) * 16) = st[i]; } }
.LBB0_447:
	s_or_saveexec_b64 s[14:15], s[16:17]
	v_mul_hi_i32 v29, v22, s47
	v_lshrrev_b32_e32 v28, 31, v29
	v_ashrrev_i32_e32 v29, 3, v29
	s_xor_b64 exec, exec, s[14:15]
	s_cbranch_execz .LBB0_456
	v_add_u32_e32 v16, v29, v28
	v_add_u32_e32 v14, s57, v16
	v_mul_lo_u32 v16, v16, 20
	v_ashrrev_i32_e32 v15, 31, v14
	v_sub_u32_e32 v16, v22, v16
	v_lshlrev_b64 v[14:15], 12, v[14:15]
	v_lshlrev_b32_e32 v16, 3, v16
	v_lshl_add_u64 v[14:15], s[20:21], 0, v[14:15]
	v_ashrrev_i32_e32 v17, 31, v16
	v_lshl_add_u64 v[14:15], v[16:17], 1, v[14:15]
	global_load_dwordx4 v[14:17], v[14:15], off
	s_or_b64 exec, exec, s[14:15]
	s_and_saveexec_b64 s[14:15], vcc
	s_xor_b64 s[14:15], exec, s[14:15]
	s_cbranch_execnz .LBB0_457
